# norm phases: shift/scale vectors requested at the top of the iteration with the row loads; no memory wait on the reuse path
# baseline (speedup 1.0000x reference)
.LBB0_157:
	v_lshlrev_b64 v[8:9], 12, v[8:9]
	v_lshl_add_u64 v[8:9], v[10:11], 0, v[8:9]
	v_lshlrev_b32_e32 v164, 2, v26
	v_lshl_add_u64 v[8:9], v[8:9], 0, v[164:165]
	global_load_dwordx4 v[20:23], v[8:9], off nt
	global_load_dwordx4 v[16:19], v[8:9], off offset:1024 nt
	global_load_dwordx4 v[12:15], v[8:9], off offset:2048 nt
	s_nop 0
	global_load_dwordx4 v[8:11], v[8:9], off offset:3072 nt
	v_add_u32_e32 v234, 0xffffe000, v40
	v_lshrrev_b32_e32 v234, 12, v234
	v_add_u32_e32 v234, 1, v234
	v_cmp_lt_i32_e64 s[100:101], s48, v40
	s_nop 1
	v_cndmask_b32_e64 v234, 0, v234, s[100:101]
	v_add_u32_e32 v234, s69, v234
	v_mov_b64_e32 v[254:255], s[4:5]
	v_mad_u64_u32 v[254:255], s[100:101], v234, s50, v[254:255]
	v_lshlrev_b32_e32 v234, 2, v26
	v_mov_b32_e32 v235, 0
	v_lshl_add_u64 v[252:253], v[254:255], 0, s[58:59]
	v_lshl_add_u64 v[254:255], v[254:255], 0, v[234:235]
	v_lshl_add_u64 v[252:253], v[252:253], 0, v[234:235]
	global_load_dwordx4 v[214:217], v[254:255], off
	global_load_dwordx4 v[218:221], v[254:255], off offset:1024
	global_load_dwordx4 v[222:225], v[254:255], off offset:2048
	global_load_dwordx4 v[226:229], v[254:255], off offset:3072
	global_load_dwordx4 v[230:233], v[252:253], off
	global_load_dwordx4 v[240:243], v[252:253], off offset:1024
	global_load_dwordx4 v[244:247], v[252:253], off offset:2048
	global_load_dwordx4 v[248:251], v[252:253], off offset:3072
	v_add_u32_e32 v50, s46, v40
	s_mov_b32 s2, 0xa000
	v_cmp_gt_i32_e64 s[34:35], s2, v50
	v_mov_b64_e32 v[66:67], v[48:49]
	v_mov_b64_e32 v[64:65], v[4:5]
	v_mov_b64_e32 v[62:63], v[46:47]
	v_mov_b64_e32 v[58:59], v[6:7]
	v_mov_b64_e32 v[60:61], v[44:45]
	v_mov_b64_e32 v[56:57], v[0:1]
	v_mov_b64_e32 v[54:55], v[42:43]
	v_mov_b64_e32 v[52:53], v[2:3]
	s_and_saveexec_b64 s[14:15], s[34:35]
	s_cbranch_execz .LBB0_167
	s_andn2_b64 vcc, exec, s[8:9]
	s_cbranch_vccnz .LBB0_160
	v_mov_b32_e32 v0, 0x21d20
	v_ashrrev_i32_e32 v51, 31, v50
	v_add_u32_e32 v0, 0, v0
	ds_read_b64 v[0:1], v0
	s_waitcnt lgkmcnt(0)
	v_readfirstlane_b32 s17, v1
	v_readfirstlane_b32 s16, v0
	v_mov_b64_e32 v[0:1], v[50:51]
	s_nop 0
	v_mov_b64_e32 v[2:3], s[16:17]
	s_cbranch_execz .LBB0_161
	s_branch .LBB0_166

.LBB0_167:
	s_or_b64 exec, exec, s[14:15]
	v_add_u32_e32 v31, 0xffffe000, v40
	v_lshrrev_b32_e32 v31, 12, v31
	v_add_u32_e32 v31, 1, v31
	v_cmp_lt_i32_e32 vcc, s48, v40
	v_mov_b64_e32 v[70:71], s[4:5]
	s_waitcnt vmcnt(3)
	v_mov_b32_e32 v86, v21
	v_cndmask_b32_e32 v31, 0, v31, vcc
	v_add_u32_e32 v31, s69, v31
	v_mad_u64_u32 v[74:75], s[6:7], v31, s50, v[70:71]
	v_lshl_add_u64 v[82:83], v[74:75], 0, s[58:59]
	v_lshl_add_u64 v[84:85], v[74:75], 0, v[164:165]
	v_lshl_add_u64 v[78:79], v[82:83], 0, v[164:165]
	s_nop 0
	s_waitcnt vmcnt(0)
	v_mov_b32_e32 v70, v198
	v_mov_b32_e32 v71, v199
	v_mov_b32_e32 v72, v200
	v_mov_b32_e32 v73, v201
	v_mov_b32_e32 v74, v214
	v_mov_b32_e32 v75, v215
	v_mov_b32_e32 v76, v216
	v_mov_b32_e32 v77, v217
	v_mov_b32_e32 v78, v230
	v_mov_b32_e32 v79, v231
	v_mov_b32_e32 v80, v232
	v_mov_b32_e32 v81, v233
	v_mov_b32_e32 v87, v17
	v_mov_b32_e32 v68, v20
	v_mov_b32_e32 v69, v16
	v_pk_mul_f32 v[86:87], v[86:87], v[86:87]
	v_mov_b32_e32 v88, v22
	v_mov_b32_e32 v89, v18
	v_pk_fma_f32 v[68:69], v[68:69], v[68:69], v[86:87]
	v_mov_b32_e32 v90, v23
	v_pk_fma_f32 v[68:69], v[88:89], v[88:89], v[68:69]
	v_mov_b32_e32 v88, v13
	v_mov_b32_e32 v89, v9
	v_mov_b32_e32 v91, v19
	v_mov_b32_e32 v86, v12
	v_mov_b32_e32 v87, v8
	v_pk_mul_f32 v[88:89], v[88:89], v[88:89]
	v_pk_fma_f32 v[68:69], v[90:91], v[90:91], v[68:69]
	v_mov_b32_e32 v90, v14
	v_mov_b32_e32 v91, v10
	v_pk_fma_f32 v[86:87], v[86:87], v[86:87], v[88:89]
	v_mov_b32_e32 v92, v15
	v_mov_b32_e32 v93, v11
	v_pk_fma_f32 v[86:87], v[90:91], v[90:91], v[86:87]
	v_add_f32_e32 v31, v68, v69
	v_pk_fma_f32 v[86:87], v[92:93], v[92:93], v[86:87]
	v_lshlrev_b32_e32 v68, 2, v30
	v_add_f32_e32 v31, v31, v86
	v_add_f32_e32 v31, v31, v87
	ds_bpermute_b32 v33, v27, v31
	v_mov_b32_e32 v69, v165
	v_lshl_add_u64 v[86:87], v[82:83], 0, v[68:69]
	s_waitcnt lgkmcnt(0)
	v_add_f32_e32 v31, v31, v33
	ds_swizzle_b32 v33, v31 offset:swizzle(SWAP,16)
	s_waitcnt lgkmcnt(0)
	v_add_f32_e32 v31, v31, v33
	ds_swizzle_b32 v33, v31 offset:swizzle(SWAP,8)
	s_waitcnt lgkmcnt(0)
	v_add_f32_e32 v31, v31, v33
	ds_swizzle_b32 v33, v31 offset:swizzle(SWAP,4)
	s_waitcnt lgkmcnt(0)
	v_add_f32_e32 v31, v31, v33
	ds_swizzle_b32 v33, v31 offset:swizzle(SWAP,2)
	s_waitcnt lgkmcnt(0)
	v_add_f32_e32 v31, v31, v33
	ds_swizzle_b32 v33, v31 offset:swizzle(SWAP,1)
	s_waitcnt lgkmcnt(0)
	v_add_f32_e32 v31, v31, v33
	v_fmamk_f32 v31, v31, 0x3a800000, v189
	v_mul_f32_e32 v33, 0x4b800000, v31
	v_cmp_gt_f32_e32 vcc, s28, v31
	v_add_f32_e32 v35, 1.0, v79
	s_nop 0
	v_cndmask_b32_e32 v31, v31, v33, vcc
	v_rsq_f32_e32 v31, v31
	v_add_f32_e32 v41, 1.0, v80
	v_add_f32_e32 v51, 1.0, v81
	v_mul_f32_e32 v33, 0x45800000, v31
	v_cndmask_b32_e32 v31, v31, v33, vcc
	v_mul_f32_e32 v20, v20, v31
	v_mul_f32_e32 v21, v21, v31
	v_mul_f32_e32 v22, v22, v31
	v_mul_f32_e32 v23, v23, v31
	v_mul_f32_e32 v20, v70, v20
	v_mul_f32_e32 v21, v71, v21
	v_add_f32_e32 v33, 1.0, v78
	v_mul_f32_e32 v22, v72, v22
	v_mul_f32_e32 v23, v73, v23
	v_fma_f32 v20, v33, v20, v74
	v_fma_f32 v21, v35, v21, v75
	v_fma_f32 v22, v22, v41, v76
	v_fmac_f32_e32 v77, v23, v51
	v_cvt_pk_bf16_f32 v20, v20, v21
	v_cvt_pk_bf16_f32 v21, v22, v77
	global_store_dwordx2 v[38:39], v[20:21], off
	v_mov_b32_e32 v70, v202
	v_mov_b32_e32 v71, v203
	v_mov_b32_e32 v72, v204
	v_mov_b32_e32 v73, v205
	v_mov_b32_e32 v74, v240
	v_mov_b32_e32 v75, v241
	v_mov_b32_e32 v76, v242
	v_mov_b32_e32 v77, v243
	v_mov_b32_e32 v78, v218
	v_mov_b32_e32 v79, v219
	v_mov_b32_e32 v80, v220
	v_mov_b32_e32 v81, v221
	v_mul_f32_e32 v16, v16, v31
	v_mul_f32_e32 v17, v17, v31
	v_mul_f32_e32 v18, v18, v31
	v_mul_f32_e32 v19, v19, v31
	v_lshlrev_b32_e32 v20, 2, v32
	v_mov_b32_e32 v21, v165
	v_lshl_add_u64 v[22:23], v[82:83], 0, v[20:21]
	v_mul_f32_e32 v12, v12, v31
	v_mul_f32_e32 v13, v13, v31
	v_mul_f32_e32 v14, v14, v31
	v_mul_f32_e32 v15, v15, v31
	v_mul_f32_e32 v8, v8, v31
	v_mul_f32_e32 v9, v9, v31
	v_mul_f32_e32 v10, v10, v31
	v_mul_f32_e32 v11, v11, v31
	v_mul_f32_e32 v16, v16, v70
	v_add_f32_e32 v33, 1.0, v74
	v_mul_f32_e32 v17, v17, v71
	v_add_f32_e32 v35, 1.0, v75
	v_mul_f32_e32 v18, v18, v72
	v_add_f32_e32 v41, 1.0, v76
	v_mul_f32_e32 v19, v19, v73
	v_add_f32_e32 v51, 1.0, v77
	v_fma_f32 v16, v16, v33, v78
	v_fma_f32 v17, v17, v35, v79
	v_fma_f32 v18, v18, v41, v80
	v_fmac_f32_e32 v81, v19, v51
	v_cvt_pk_bf16_f32 v16, v16, v17
	v_cvt_pk_bf16_f32 v17, v18, v81
	global_store_dwordx2 v[38:39], v[16:17], off offset:512
	v_mov_b32_e32 v70, v206
	v_mov_b32_e32 v71, v207
	v_mov_b32_e32 v72, v208
	v_mov_b32_e32 v73, v209
	v_mov_b32_e32 v74, v244
	v_mov_b32_e32 v75, v245
	v_mov_b32_e32 v76, v246
	v_mov_b32_e32 v77, v247
	v_mov_b32_e32 v78, v222
	v_mov_b32_e32 v79, v223
	v_mov_b32_e32 v80, v224
	v_mov_b32_e32 v81, v225
	v_lshlrev_b32_e32 v16, 2, v34
	v_mov_b32_e32 v17, v165
	v_lshl_add_u64 v[18:19], v[82:83], 0, v[16:17]
	v_mul_f32_e32 v12, v12, v70
	v_add_f32_e32 v22, 1.0, v74
	v_mul_f32_e32 v13, v13, v71
	v_add_f32_e32 v23, 1.0, v75
	v_mul_f32_e32 v14, v14, v72
	v_add_f32_e32 v33, 1.0, v76
	v_mul_f32_e32 v15, v15, v73
	v_add_f32_e32 v35, 1.0, v77
	v_fma_f32 v12, v12, v22, v78
	v_fma_f32 v13, v13, v23, v79
	v_fma_f32 v14, v14, v33, v80
	v_fmac_f32_e32 v81, v15, v35
	v_cvt_pk_bf16_f32 v12, v12, v13
	v_cvt_pk_bf16_f32 v13, v14, v81
	global_store_dwordx2 v[38:39], v[12:13], off offset:1024
	v_mov_b32_e32 v12, v210
	v_mov_b32_e32 v13, v211
	v_mov_b32_e32 v14, v212
	v_mov_b32_e32 v15, v213
	s_nop 0
	v_mov_b32_e32 v70, v248
	v_mov_b32_e32 v71, v249
	v_mov_b32_e32 v72, v250
	v_mov_b32_e32 v73, v251
	v_mov_b32_e32 v74, v226
	v_mov_b32_e32 v75, v227
	v_mov_b32_e32 v76, v228
	v_mov_b32_e32 v77, v229
	v_mul_f32_e32 v8, v8, v12
	v_add_f32_e32 v12, 1.0, v70
	v_mul_f32_e32 v9, v9, v13
	v_add_f32_e32 v13, 1.0, v71
	v_mul_f32_e32 v10, v10, v14
	v_add_f32_e32 v14, 1.0, v72
	v_mul_f32_e32 v11, v11, v15
	v_add_f32_e32 v15, 1.0, v73
	v_fma_f32 v8, v8, v12, v74
	v_fma_f32 v9, v9, v13, v75
	v_fma_f32 v10, v10, v14, v76
	v_fmac_f32_e32 v77, v11, v15
	v_cvt_pk_bf16_f32 v8, v8, v9
	v_cvt_pk_bf16_f32 v9, v10, v77
	global_store_dwordx2 v[38:39], v[8:9], off offset:1536
	s_and_saveexec_b64 s[14:15], s[34:35]
	s_cbranch_execz .LBB0_148
	v_add_u32_e32 v8, 0xffffe000, v50
	v_lshrrev_b32_e32 v8, 12, v8
	v_add_u32_e32 v8, 1, v8
	v_cmp_lt_i32_e32 vcc, s48, v50
	v_mov_b64_e32 v[12:13], s[4:5]
	v_pk_mul_f32 v[60:61], v[60:61], v[60:61]
	v_cndmask_b32_e32 v8, 0, v8, vcc
	v_add_u32_e32 v14, s69, v8
	v_mad_u64_u32 v[18:19], s[6:7], v14, s50, v[12:13]
	v_lshl_add_u64 v[22:23], v[18:19], 0, s[58:59]
	v_lshl_add_u64 v[12:13], v[22:23], 0, v[164:165]
	v_lshl_add_u64 v[74:75], v[18:19], 0, v[164:165]
	v_pk_mul_f32 v[18:19], v[66:67], v[66:67]
	v_mov_b32_e32 v254, v12
	v_mov_b32_e32 v255, v13
	v_cmp_ne_u64_e32 vcc, v[254:255], v[252:253]
	s_nop 1
	s_and_b64 vcc, exec, vcc
	s_cbranch_vccz .Lnorm_same_cond_1
	global_load_dwordx4 v[214:217], v[74:75], off
	global_load_dwordx4 v[218:221], v[74:75], off offset:1024
	global_load_dwordx4 v[222:225], v[74:75], off offset:2048
	global_load_dwordx4 v[226:229], v[74:75], off offset:3072
	global_load_dwordx4 v[230:233], v[254:255], off
	global_load_dwordx4 v[240:243], v[254:255], off offset:1024
	global_load_dwordx4 v[244:247], v[254:255], off offset:2048
	global_load_dwordx4 v[248:251], v[254:255], off offset:3072
	s_waitcnt vmcnt(0)
.Lnorm_same_cond_1:
	v_mov_b32_e32 v8, v198
	v_mov_b32_e32 v9, v199
	v_mov_b32_e32 v10, v200
	v_mov_b32_e32 v11, v201
	v_mov_b32_e32 v12, v230
	v_mov_b32_e32 v13, v231
	v_mov_b32_e32 v14, v232
	v_mov_b32_e32 v15, v233
	v_mov_b32_e32 v70, v214
	v_mov_b32_e32 v71, v215
	v_mov_b32_e32 v72, v216
	v_mov_b32_e32 v73, v217
	v_pk_fma_f32 v[18:19], v[64:65], v[64:65], v[18:19]
	v_pk_fma_f32 v[56:57], v[56:57], v[56:57], v[60:61]
	v_pk_fma_f32 v[18:19], v[62:63], v[62:63], v[18:19]
	v_pk_fma_f32 v[54:55], v[54:55], v[54:55], v[56:57]
	v_pk_fma_f32 v[18:19], v[58:59], v[58:59], v[18:19]
	v_pk_fma_f32 v[52:53], v[52:53], v[52:53], v[54:55]
	v_add_f32_e32 v18, v18, v19
	v_add_f32_e32 v18, v53, v18
	v_add_f32_e32 v18, v52, v18
	ds_bpermute_b32 v19, v27, v18
	v_ashrrev_i32_e32 v51, 31, v50
	v_lshl_add_u64 v[16:17], v[22:23], 0, v[16:17]
	s_waitcnt lgkmcnt(0)
	v_add_f32_e32 v18, v18, v19
	ds_swizzle_b32 v19, v18 offset:swizzle(SWAP,16)
	s_waitcnt lgkmcnt(0)
	v_add_f32_e32 v18, v18, v19
	ds_swizzle_b32 v19, v18 offset:swizzle(SWAP,8)
	s_waitcnt lgkmcnt(0)
	v_add_f32_e32 v18, v18, v19
	ds_swizzle_b32 v19, v18 offset:swizzle(SWAP,4)
	s_waitcnt lgkmcnt(0)
	v_add_f32_e32 v18, v18, v19
	ds_swizzle_b32 v19, v18 offset:swizzle(SWAP,2)
	s_waitcnt lgkmcnt(0)
	v_add_f32_e32 v18, v18, v19
	ds_swizzle_b32 v19, v18 offset:swizzle(SWAP,1)
	s_waitcnt lgkmcnt(0)
	v_add_f32_e32 v18, v18, v19
	v_fmamk_f32 v18, v18, 0x3a800000, v189
	v_mul_f32_e32 v19, 0x4b800000, v18
	v_cmp_gt_f32_e32 vcc, s28, v18
	v_add_f32_e32 v12, 1.0, v12
	s_nop 0
	v_cndmask_b32_e32 v18, v18, v19, vcc
	v_rsq_f32_e32 v31, v18
	v_lshlrev_b64 v[18:19], 11, v[50:51]
	v_add_f32_e32 v13, 1.0, v13
	v_lshl_add_u64 v[54:55], v[36:37], 0, v[18:19]
	v_mul_f32_e32 v33, 0x45800000, v31
	v_cndmask_b32_e32 v31, v31, v33, vcc
	v_mul_f32_e32 v33, v49, v31
	v_mul_f32_e32 v35, v5, v31
	v_mul_f32_e32 v41, v47, v31
	v_mul_f32_e32 v50, v7, v31
	v_mul_f32_e32 v8, v8, v33
	v_mul_f32_e32 v9, v9, v35
	v_mul_f32_e32 v10, v10, v41
	v_mul_f32_e32 v11, v11, v50
	v_add_f32_e32 v14, 1.0, v14
	v_add_f32_e32 v15, 1.0, v15
	v_fma_f32 v8, v12, v8, v70
	v_fma_f32 v9, v13, v9, v71
	v_fma_f32 v10, v10, v14, v72
	v_fmac_f32_e32 v73, v11, v15
	v_cvt_pk_bf16_f32 v8, v8, v9
	v_cvt_pk_bf16_f32 v9, v10, v73
	global_store_dwordx2 v[54:55], v[8:9], off
	v_lshl_add_u64 v[18:19], v[22:23], 0, v[68:69]
	v_mov_b32_e32 v8, v202
	v_mov_b32_e32 v9, v203
	v_mov_b32_e32 v10, v204
	v_mov_b32_e32 v11, v205
	v_mov_b32_e32 v12, v240
	v_mov_b32_e32 v13, v241
	v_mov_b32_e32 v14, v242
	v_mov_b32_e32 v15, v243
	v_mov_b32_e32 v50, v218
	v_mov_b32_e32 v51, v219
	v_mov_b32_e32 v52, v220
	v_mov_b32_e32 v53, v221
	v_lshl_add_u64 v[18:19], v[22:23], 0, v[20:21]
	v_mul_f32_e32 v20, v48, v31
	v_mul_f32_e32 v21, v4, v31
	v_mul_f32_e32 v33, v46, v31
	v_mul_f32_e32 v35, v6, v31
	v_mul_f32_e32 v22, v45, v31
	v_mul_f32_e32 v23, v1, v31
	v_mul_f32_e32 v8, v20, v8
	v_add_f32_e32 v12, 1.0, v12
	v_mul_f32_e32 v9, v21, v9
	v_add_f32_e32 v13, 1.0, v13
	v_mul_f32_e32 v10, v33, v10
	v_add_f32_e32 v14, 1.0, v14
	v_mul_f32_e32 v11, v35, v11
	v_add_f32_e32 v15, 1.0, v15
	v_fma_f32 v8, v8, v12, v50
	v_fma_f32 v9, v9, v13, v51
	v_fma_f32 v10, v10, v14, v52
	v_fmac_f32_e32 v53, v11, v15
	v_cvt_pk_bf16_f32 v8, v8, v9
	v_cvt_pk_bf16_f32 v9, v10, v53
	global_store_dwordx2 v[54:55], v[8:9], off offset:512
	v_mov_b32_e32 v8, v206
	v_mov_b32_e32 v9, v207
	v_mov_b32_e32 v10, v208
	v_mov_b32_e32 v11, v209
	s_nop 0
	v_mov_b32_e32 v12, v244
	v_mov_b32_e32 v13, v245
	v_mov_b32_e32 v14, v246
	v_mov_b32_e32 v15, v247
	s_nop 0
	v_mov_b32_e32 v18, v222
	v_mov_b32_e32 v19, v223
	v_mov_b32_e32 v20, v224
	v_mov_b32_e32 v21, v225
	v_mul_f32_e32 v33, v43, v31
	v_mul_f32_e32 v35, v3, v31
	v_mul_f32_e32 v8, v22, v8
	v_add_f32_e32 v12, 1.0, v12
	v_mul_f32_e32 v9, v23, v9
	v_add_f32_e32 v13, 1.0, v13
	v_mul_f32_e32 v10, v33, v10
	v_add_f32_e32 v14, 1.0, v14
	v_mul_f32_e32 v11, v35, v11
	v_add_f32_e32 v15, 1.0, v15
	v_fma_f32 v8, v8, v12, v18
	v_fma_f32 v9, v9, v13, v19
	v_fma_f32 v10, v10, v14, v20
	v_fmac_f32_e32 v21, v11, v15
	v_cvt_pk_bf16_f32 v8, v8, v9
	v_cvt_pk_bf16_f32 v9, v10, v21
	global_store_dwordx2 v[54:55], v[8:9], off offset:1024
	v_mov_b32_e32 v8, v210
	v_mov_b32_e32 v9, v211
	v_mov_b32_e32 v10, v212
	v_mov_b32_e32 v11, v213
	s_nop 0
	v_mov_b32_e32 v12, v248
	v_mov_b32_e32 v13, v249
	v_mov_b32_e32 v14, v250
	v_mov_b32_e32 v15, v251
	s_nop 0
	v_mov_b32_e32 v16, v226
	v_mov_b32_e32 v17, v227
	v_mov_b32_e32 v18, v228
	v_mov_b32_e32 v19, v229
	v_mul_f32_e32 v20, v44, v31
	v_mul_f32_e32 v21, v0, v31
	v_mul_f32_e32 v22, v42, v31
	v_mul_f32_e32 v23, v2, v31
	v_mul_f32_e32 v8, v20, v8
	v_add_f32_e32 v12, 1.0, v12
	v_mul_f32_e32 v9, v21, v9
	v_add_f32_e32 v13, 1.0, v13
	v_mul_f32_e32 v10, v22, v10
	v_add_f32_e32 v14, 1.0, v14
	v_mul_f32_e32 v11, v23, v11
	v_add_f32_e32 v15, 1.0, v15
	v_fma_f32 v8, v8, v12, v16
	v_fma_f32 v9, v9, v13, v17
	v_fma_f32 v10, v10, v14, v18
	v_fmac_f32_e32 v19, v11, v15
	v_cvt_pk_bf16_f32 v8, v8, v9
	v_cvt_pk_bf16_f32 v9, v10, v19
	global_store_dwordx2 v[54:55], v[8:9], off offset:1536
	s_branch .LBB0_148

.LBB0_1332:
	v_mov_b32_e32 v8, 0x21d20
	v_add_u32_e32 v60, s46, v28
	v_add_u32_e32 v8, 0, v8
	ds_read_b64 v[8:9], v8
	s_mov_b32 s2, 0xa000
	v_cmp_gt_i32_e32 vcc, s2, v60
	v_ashrrev_i32_e32 v61, 31, v60
	v_lshlrev_b32_e32 v164, 2, v30
	s_waitcnt lgkmcnt(0)
	v_readfirstlane_b32 s7, v9
	v_readfirstlane_b32 s6, v8
	v_mov_b64_e32 v[62:63], v[52:53]
	v_mov_b64_e32 v[64:65], v[2:3]
	v_lshl_add_u64 v[8:9], s[6:7], 0, v[50:51]
	global_load_dwordx4 v[20:23], v[8:9], off nt
	global_load_dwordx4 v[16:19], v[8:9], off offset:1024 nt
	global_load_dwordx4 v[12:15], v[8:9], off offset:2048 nt
	s_nop 0
	global_load_dwordx4 v[8:11], v[8:9], off offset:3072 nt
	v_add_u32_e32 v234, 0xffffe000, v28
	v_lshrrev_b32_e32 v234, 12, v234
	v_add_u32_e32 v234, 1, v234
	v_cmp_lt_i32_e64 s[100:101], s48, v28
	s_nop 1
	v_cndmask_b32_e64 v234, 0, v234, s[100:101]
	v_add_u32_e32 v234, s86, v234
	v_mov_b64_e32 v[254:255], s[4:5]
	v_mad_u64_u32 v[254:255], s[100:101], v234, s50, v[254:255]
	v_lshlrev_b32_e32 v234, 2, v30
	v_mov_b32_e32 v235, 0
	v_lshl_add_u64 v[252:253], v[254:255], 0, s[58:59]
	v_lshl_add_u64 v[254:255], v[254:255], 0, v[234:235]
	v_lshl_add_u64 v[252:253], v[252:253], 0, v[234:235]
	global_load_dwordx4 v[214:217], v[254:255], off
	global_load_dwordx4 v[218:221], v[254:255], off offset:1024
	global_load_dwordx4 v[222:225], v[254:255], off offset:2048
	global_load_dwordx4 v[226:229], v[254:255], off offset:3072
	global_load_dwordx4 v[230:233], v[252:253], off
	global_load_dwordx4 v[240:243], v[252:253], off offset:1024
	global_load_dwordx4 v[244:247], v[252:253], off offset:2048
	global_load_dwordx4 v[248:251], v[252:253], off offset:3072
	v_mov_b64_e32 v[66:67], v[54:55]
	v_mov_b64_e32 v[68:69], v[0:1]
	v_mov_b64_e32 v[70:71], v[56:57]
	v_mov_b64_e32 v[72:73], v[6:7]
	v_mov_b64_e32 v[74:75], v[58:59]
	v_mov_b64_e32 v[76:77], v[4:5]
	s_and_saveexec_b64 s[10:11], vcc
	s_cbranch_execz .LBB0_1334
	v_mov_b32_e32 v0, 0x21d20
	v_lshlrev_b64 v[2:3], 12, v[60:61]
	v_add_u32_e32 v0, 0, v0
	ds_read_b64 v[0:1], v0
	s_waitcnt lgkmcnt(0)
	v_readfirstlane_b32 s7, v1
	v_readfirstlane_b32 s6, v0
	s_nop 1
	v_lshl_add_u64 v[0:1], s[6:7], 0, v[2:3]
	v_lshl_add_u64 v[52:53], v[0:1], 0, v[164:165]
	global_load_dwordx4 v[0:3], v[52:53], off offset:3072 nt
	global_load_dwordx4 v[24:27], v[52:53], off offset:2048 nt
	global_load_dwordx4 v[4:7], v[52:53], off offset:1024 nt
	global_load_dwordx4 v[78:81], v[52:53], off nt
	s_waitcnt vmcnt(3)
	v_mov_b32_e32 v62, v3
	s_waitcnt vmcnt(2)
	v_mov_b32_e32 v63, v27
	v_mov_b32_e32 v64, v2
	v_mov_b32_e32 v65, v26
	v_mov_b32_e32 v66, v1
	v_mov_b32_e32 v67, v25
	v_mov_b32_e32 v68, v0
	v_mov_b32_e32 v69, v24
	s_waitcnt vmcnt(1)
	v_mov_b32_e32 v70, v7
	s_waitcnt vmcnt(0)
	v_mov_b32_e32 v71, v81
	v_mov_b32_e32 v72, v6
	v_mov_b32_e32 v73, v80
	v_mov_b32_e32 v74, v5
	v_mov_b32_e32 v75, v79
	v_mov_b32_e32 v76, v4
	v_mov_b32_e32 v77, v78
	v_mov_b32_e32 v52, v3
	v_mov_b32_e32 v53, v27
	v_mov_b32_e32 v3, v26
	v_mov_b32_e32 v54, v1
	v_mov_b32_e32 v55, v25
	v_mov_b32_e32 v1, v24
	v_mov_b32_e32 v56, v7
	v_mov_b32_e32 v57, v81
	v_mov_b32_e32 v7, v80
	v_mov_b32_e32 v58, v5
	v_mov_b32_e32 v59, v79
	v_mov_b32_e32 v5, v78
.LBB0_1334:
	s_or_b64 exec, exec, s[10:11]
	s_waitcnt vmcnt(3)
	v_mov_b32_e32 v26, v21
	s_waitcnt vmcnt(2)
	v_mov_b32_e32 v27, v17
	v_mov_b32_e32 v24, v20
	v_mov_b32_e32 v25, v16
	v_pk_mul_f32 v[26:27], v[26:27], v[26:27]
	v_mov_b32_e32 v78, v22
	v_mov_b32_e32 v79, v18
	v_pk_fma_f32 v[24:25], v[24:25], v[24:25], v[26:27]
	v_mov_b32_e32 v80, v23
	v_pk_fma_f32 v[24:25], v[78:79], v[78:79], v[24:25]
	s_waitcnt vmcnt(1)
	v_mov_b32_e32 v78, v13
	s_waitcnt vmcnt(0)
	v_mov_b32_e32 v79, v9
	v_mov_b32_e32 v81, v19
	v_mov_b32_e32 v26, v12
	v_mov_b32_e32 v27, v8
	v_pk_mul_f32 v[78:79], v[78:79], v[78:79]
	v_pk_fma_f32 v[24:25], v[80:81], v[80:81], v[24:25]
	v_mov_b32_e32 v80, v14
	v_mov_b32_e32 v81, v10
	v_pk_fma_f32 v[26:27], v[26:27], v[26:27], v[78:79]
	v_mov_b32_e32 v82, v15
	v_mov_b32_e32 v83, v11
	v_pk_fma_f32 v[26:27], v[80:81], v[80:81], v[26:27]
	v_add_f32_e32 v24, v24, v25
	v_pk_fma_f32 v[26:27], v[82:83], v[82:83], v[26:27]
	s_nop 0
	v_add_f32_e32 v24, v24, v26
	v_add_f32_e32 v24, v24, v27
	ds_bpermute_b32 v25, v31, v24
	s_waitcnt lgkmcnt(0)
	v_add_f32_e32 v24, v24, v25
	ds_swizzle_b32 v25, v24 offset:swizzle(SWAP,16)
	s_waitcnt lgkmcnt(0)
	v_add_f32_e32 v24, v24, v25
	ds_swizzle_b32 v25, v24 offset:swizzle(SWAP,8)
	s_waitcnt lgkmcnt(0)
	v_add_f32_e32 v24, v24, v25
	ds_swizzle_b32 v25, v24 offset:swizzle(SWAP,4)
	s_waitcnt lgkmcnt(0)
	v_add_f32_e32 v24, v24, v25
	ds_swizzle_b32 v25, v24 offset:swizzle(SWAP,2)
	s_waitcnt lgkmcnt(0)
	v_add_f32_e32 v24, v24, v25
	ds_swizzle_b32 v25, v24 offset:swizzle(SWAP,1)
	s_waitcnt lgkmcnt(0)
	v_add_f32_e32 v24, v24, v25
	v_fmamk_f32 v24, v24, 0x3a800000, v189
	v_cmp_gt_f32_e64 s[34:35], s28, v24
	v_mul_f32_e32 v25, 0x4b800000, v24
	s_nop 0
	v_cndmask_b32_e64 v24, v24, v25, s[34:35]
	v_rsq_f32_e32 v24, v24
	s_nop 0
	v_mul_f32_e32 v25, 0x45800000, v24
	v_cndmask_b32_e64 v29, v24, v25, s[34:35]
	v_add_u32_e32 v24, 0xffffe000, v28
	v_lshrrev_b32_e32 v24, 12, v24
	v_add_u32_e32 v24, 1, v24
	v_cmp_lt_i32_e64 s[34:35], s48, v28
	v_mul_f32_e32 v20, v20, v29
	v_mul_f32_e32 v21, v21, v29
	v_cndmask_b32_e64 v24, 0, v24, s[34:35]
	v_add_u32_e32 v26, s86, v24
	v_mov_b64_e32 v[24:25], s[4:5]
	v_mad_u64_u32 v[78:79], s[6:7], v26, s50, v[24:25]
	v_lshl_add_u64 v[80:81], v[78:79], 0, s[58:59]
	v_lshl_add_u64 v[82:83], v[78:79], 0, v[164:165]
	v_lshl_add_u64 v[78:79], v[80:81], 0, v[164:165]
	s_waitcnt vmcnt(0)
	v_mov_b32_e32 v24, v198
	v_mov_b32_e32 v25, v199
	v_mov_b32_e32 v26, v200
	v_mov_b32_e32 v27, v201
	v_mov_b32_e32 v84, v214
	v_mov_b32_e32 v85, v215
	v_mov_b32_e32 v86, v216
	v_mov_b32_e32 v87, v217
	v_mov_b32_e32 v88, v230
	v_mov_b32_e32 v89, v231
	v_mov_b32_e32 v90, v232
	v_mov_b32_e32 v91, v233
	v_mul_f32_e32 v22, v22, v29
	v_mul_f32_e32 v23, v23, v29
	v_lshlrev_b32_e32 v78, 2, v34
	v_mov_b32_e32 v79, v165
	v_mul_f32_e32 v16, v16, v29
	v_mul_f32_e32 v17, v17, v29
	v_mul_f32_e32 v18, v18, v29
	v_mul_f32_e32 v19, v19, v29
	v_mul_f32_e32 v12, v12, v29
	v_mul_f32_e32 v13, v13, v29
	v_mul_f32_e32 v14, v14, v29
	v_mul_f32_e32 v15, v15, v29
	v_mul_f32_e32 v8, v8, v29
	v_mul_f32_e32 v9, v9, v29
	v_mul_f32_e32 v10, v10, v29
	v_mul_f32_e32 v11, v11, v29
	v_mul_f32_e32 v20, v24, v20
	v_mul_f32_e32 v21, v25, v21
	v_add_f32_e32 v24, 1.0, v88
	v_fma_f32 v20, v24, v20, v84
	v_add_f32_e32 v24, 1.0, v89
	v_fma_f32 v21, v24, v21, v85
	v_mul_f32_e32 v22, v26, v22
	v_add_f32_e32 v24, 1.0, v90
	v_fma_f32 v22, v22, v24, v86
	v_mul_f32_e32 v23, v27, v23
	v_add_f32_e32 v24, 1.0, v91
	v_fmac_f32_e32 v87, v23, v24
	v_cvt_pk_bf16_f32 v20, v20, v21
	v_cvt_pk_bf16_f32 v21, v22, v87
	global_store_dwordx2 v[48:49], v[20:21], off
	v_lshl_add_u64 v[84:85], v[80:81], 0, v[78:79]
	v_mov_b32_e32 v24, v202
	v_mov_b32_e32 v25, v203
	v_mov_b32_e32 v26, v204
	v_mov_b32_e32 v27, v205
	v_mov_b32_e32 v20, v218
	v_mov_b32_e32 v21, v219
	v_mov_b32_e32 v22, v220
	v_mov_b32_e32 v23, v221
	v_mul_f32_e32 v16, v16, v24
	v_mov_b32_e32 v84, v240
	v_mov_b32_e32 v85, v241
	v_mov_b32_e32 v86, v242
	v_mov_b32_e32 v87, v243
	v_mul_f32_e32 v17, v17, v25
	v_mul_f32_e32 v18, v18, v26
	v_mul_f32_e32 v19, v19, v27
	v_add_f32_e32 v24, 1.0, v84
	v_fma_f32 v16, v16, v24, v20
	v_add_f32_e32 v20, 1.0, v85
	v_fma_f32 v17, v17, v20, v21
	v_add_f32_e32 v20, 1.0, v86
	v_fma_f32 v18, v18, v20, v22
	v_add_f32_e32 v20, 1.0, v87
	v_fmac_f32_e32 v23, v19, v20
	v_lshlrev_b32_e32 v20, 2, v38
	v_mov_b32_e32 v21, v165
	v_cvt_pk_bf16_f32 v16, v16, v17
	v_cvt_pk_bf16_f32 v17, v18, v23
	global_store_dwordx2 v[48:49], v[16:17], off offset:512
	v_lshl_add_u64 v[26:27], v[80:81], 0, v[20:21]
	v_mov_b32_e32 v16, v206
	v_mov_b32_e32 v17, v207
	v_mov_b32_e32 v18, v208
	v_mov_b32_e32 v19, v209
	v_mov_b32_e32 v22, v222
	v_mov_b32_e32 v23, v223
	v_mov_b32_e32 v24, v224
	v_mov_b32_e32 v25, v225
	v_mov_b32_e32 v84, v244
	v_mov_b32_e32 v85, v245
	v_mov_b32_e32 v86, v246
	v_mov_b32_e32 v87, v247
	v_mul_f32_e32 v12, v12, v16
	v_mul_f32_e32 v13, v13, v17
	v_add_f32_e32 v16, 1.0, v84
	v_fma_f32 v12, v12, v16, v22
	v_add_f32_e32 v16, 1.0, v85
	v_fma_f32 v13, v13, v16, v23
	v_mul_f32_e32 v14, v14, v18
	v_add_f32_e32 v16, 1.0, v86
	v_fma_f32 v14, v14, v16, v24
	v_mul_f32_e32 v15, v15, v19
	v_add_f32_e32 v16, 1.0, v87
	v_fmac_f32_e32 v25, v15, v16
	v_lshlrev_b32_e32 v22, 2, v42
	v_mov_b32_e32 v23, v165
	v_cvt_pk_bf16_f32 v12, v12, v13
	v_cvt_pk_bf16_f32 v13, v14, v25
	global_store_dwordx2 v[48:49], v[12:13], off offset:1024
	v_lshl_add_u64 v[24:25], v[80:81], 0, v[22:23]
	v_mov_b32_e32 v16, v210
	v_mov_b32_e32 v17, v211
	v_mov_b32_e32 v18, v212
	v_mov_b32_e32 v19, v213
	v_mov_b32_e32 v12, v226
	v_mov_b32_e32 v13, v227
	v_mov_b32_e32 v14, v228
	v_mov_b32_e32 v15, v229
	v_mul_f32_e32 v8, v8, v16
	v_mov_b32_e32 v24, v248
	v_mov_b32_e32 v25, v249
	v_mov_b32_e32 v26, v250
	v_mov_b32_e32 v27, v251
	v_mul_f32_e32 v9, v9, v17
	v_mul_f32_e32 v10, v10, v18
	v_mul_f32_e32 v11, v11, v19
	v_add_f32_e32 v16, 1.0, v24
	v_fma_f32 v8, v8, v16, v12
	v_add_f32_e32 v12, 1.0, v25
	v_fma_f32 v9, v9, v12, v13
	v_add_f32_e32 v12, 1.0, v26
	v_fma_f32 v10, v10, v12, v14
	v_add_f32_e32 v12, 1.0, v27
	v_fmac_f32_e32 v15, v11, v12
	v_cvt_pk_bf16_f32 v8, v8, v9
	v_cvt_pk_bf16_f32 v9, v10, v15
	global_store_dwordx2 v[48:49], v[8:9], off offset:1536
	s_and_saveexec_b64 s[10:11], vcc
	s_cbranch_execz .LBB0_1331
	v_pk_mul_f32 v[8:9], v[76:77], v[76:77]
	v_pk_mul_f32 v[10:11], v[68:69], v[68:69]
	v_pk_fma_f32 v[8:9], v[74:75], v[74:75], v[8:9]
	v_pk_fma_f32 v[10:11], v[66:67], v[66:67], v[10:11]
	v_pk_fma_f32 v[8:9], v[72:73], v[72:73], v[8:9]
	v_pk_fma_f32 v[10:11], v[64:65], v[64:65], v[10:11]
	v_pk_fma_f32 v[8:9], v[70:71], v[70:71], v[8:9]
	v_pk_fma_f32 v[10:11], v[62:63], v[62:63], v[10:11]
	v_add_f32_e32 v8, v8, v9
	v_add_f32_e32 v8, v11, v8
	v_add_f32_e32 v8, v10, v8
	ds_bpermute_b32 v9, v31, v8
	v_lshlrev_b64 v[14:15], 11, v[60:61]
	s_waitcnt lgkmcnt(0)
	v_add_f32_e32 v8, v8, v9
	ds_swizzle_b32 v9, v8 offset:swizzle(SWAP,16)
	s_waitcnt lgkmcnt(0)
	v_add_f32_e32 v8, v8, v9
	ds_swizzle_b32 v9, v8 offset:swizzle(SWAP,8)
	s_waitcnt lgkmcnt(0)
	v_add_f32_e32 v8, v8, v9
	ds_swizzle_b32 v9, v8 offset:swizzle(SWAP,4)
	s_waitcnt lgkmcnt(0)
	v_add_f32_e32 v8, v8, v9
	ds_swizzle_b32 v9, v8 offset:swizzle(SWAP,2)
	s_waitcnt lgkmcnt(0)
	v_add_f32_e32 v8, v8, v9
	ds_swizzle_b32 v9, v8 offset:swizzle(SWAP,1)
	s_waitcnt lgkmcnt(0)
	v_add_f32_e32 v8, v8, v9
	v_fmamk_f32 v8, v8, 0x3a800000, v189
	v_cmp_gt_f32_e32 vcc, s28, v8
	v_mul_f32_e32 v9, 0x4b800000, v8
	s_nop 0
	v_cndmask_b32_e32 v8, v8, v9, vcc
	v_rsq_f32_e32 v8, v8
	s_nop 0
	v_mul_f32_e32 v9, 0x45800000, v8
	v_cndmask_b32_e32 v24, v8, v9, vcc
	v_add_u32_e32 v8, 0xffffe000, v60
	v_lshrrev_b32_e32 v8, 12, v8
	v_add_u32_e32 v8, 1, v8
	v_cmp_lt_i32_e32 vcc, s48, v60
	s_nop 1
	v_cndmask_b32_e32 v8, 0, v8, vcc
	v_add_u32_e32 v10, s86, v8
	v_mov_b64_e32 v[8:9], s[4:5]
	v_mad_u64_u32 v[8:9], s[6:7], v10, s50, v[8:9]
	v_lshl_add_u64 v[16:17], v[8:9], 0, s[58:59]
	v_lshl_add_u64 v[8:9], v[8:9], 0, v[164:165]
	v_lshl_add_u64 v[18:19], v[16:17], 0, v[164:165]
	v_mov_b32_e32 v254, v18
	v_mov_b32_e32 v255, v19
	v_cmp_ne_u64_e32 vcc, v[254:255], v[252:253]
	s_nop 1
	s_and_b64 vcc, exec, vcc
	s_cbranch_vccz .Lnorm_same_cond_2
	global_load_dwordx4 v[214:217], v[8:9], off
	global_load_dwordx4 v[218:221], v[8:9], off offset:1024
	global_load_dwordx4 v[222:225], v[8:9], off offset:2048
	global_load_dwordx4 v[226:229], v[8:9], off offset:3072
	global_load_dwordx4 v[230:233], v[254:255], off
	global_load_dwordx4 v[240:243], v[254:255], off offset:1024
	global_load_dwordx4 v[244:247], v[254:255], off offset:2048
	global_load_dwordx4 v[248:251], v[254:255], off offset:3072
	s_waitcnt vmcnt(0)
.Lnorm_same_cond_2:
	v_mov_b32_e32 v10, v198
	v_mov_b32_e32 v11, v199
	v_mov_b32_e32 v12, v200
	v_mov_b32_e32 v13, v201
	v_mov_b32_e32 v60, v214
	v_mov_b32_e32 v61, v215
	v_mov_b32_e32 v62, v216
	v_mov_b32_e32 v63, v217
	v_mov_b32_e32 v64, v230
	v_mov_b32_e32 v65, v231
	v_mov_b32_e32 v66, v232
	v_mov_b32_e32 v67, v233
	v_mul_f32_e32 v18, v5, v24
	v_mul_f32_e32 v10, v10, v18
	v_add_f32_e32 v18, 1.0, v64
	v_fma_f32 v10, v18, v10, v60
	v_mul_f32_e32 v18, v59, v24
	v_mul_f32_e32 v11, v11, v18
	v_add_f32_e32 v18, 1.0, v65
	v_fma_f32 v11, v18, v11, v61
	v_mul_f32_e32 v18, v7, v24
	v_mul_f32_e32 v12, v12, v18
	v_add_f32_e32 v18, 1.0, v66
	v_fma_f32 v12, v12, v18, v62
	v_mul_f32_e32 v18, v57, v24
	v_mul_f32_e32 v13, v13, v18
	v_add_f32_e32 v18, 1.0, v67
	v_fmac_f32_e32 v63, v13, v18
	v_lshl_add_u64 v[18:19], v[46:47], 0, v[14:15]
	v_cvt_pk_bf16_f32 v10, v10, v11
	v_cvt_pk_bf16_f32 v11, v12, v63
	global_store_dwordx2 v[18:19], v[10:11], off
	v_lshl_add_u64 v[14:15], v[16:17], 0, v[78:79]
	v_mov_b32_e32 v10, v202
	v_mov_b32_e32 v11, v203
	v_mov_b32_e32 v12, v204
	v_mov_b32_e32 v13, v205
	v_mov_b32_e32 v60, v218
	v_mov_b32_e32 v61, v219
	v_mov_b32_e32 v62, v220
	v_mov_b32_e32 v63, v221
	v_mov_b32_e32 v64, v240
	v_mov_b32_e32 v65, v241
	v_mov_b32_e32 v66, v242
	v_mov_b32_e32 v67, v243
	v_mul_f32_e32 v14, v4, v24
	v_mul_f32_e32 v10, v14, v10
	v_add_f32_e32 v14, 1.0, v64
	v_fma_f32 v10, v10, v14, v60
	v_mul_f32_e32 v14, v58, v24
	v_mul_f32_e32 v11, v14, v11
	v_add_f32_e32 v14, 1.0, v65
	v_fma_f32 v11, v11, v14, v61
	v_mul_f32_e32 v14, v6, v24
	v_mul_f32_e32 v12, v14, v12
	v_add_f32_e32 v14, 1.0, v66
	v_fma_f32 v12, v12, v14, v62
	v_mul_f32_e32 v14, v56, v24
	v_mul_f32_e32 v13, v14, v13
	v_add_f32_e32 v14, 1.0, v67
	v_fmac_f32_e32 v63, v13, v14
	v_cvt_pk_bf16_f32 v10, v10, v11
	v_cvt_pk_bf16_f32 v11, v12, v63
	global_store_dwordx2 v[18:19], v[10:11], off offset:512
	v_lshl_add_u64 v[14:15], v[16:17], 0, v[20:21]
	v_mov_b32_e32 v10, v206
	v_mov_b32_e32 v11, v207
	v_mov_b32_e32 v12, v208
	v_mov_b32_e32 v13, v209
	v_mov_b32_e32 v60, v222
	v_mov_b32_e32 v61, v223
	v_mov_b32_e32 v62, v224
	v_mov_b32_e32 v63, v225
	v_mov_b32_e32 v64, v244
	v_mov_b32_e32 v65, v245
	v_mov_b32_e32 v66, v246
	v_mov_b32_e32 v67, v247
	v_mul_f32_e32 v14, v1, v24
	v_lshl_add_u64 v[16:17], v[16:17], 0, v[22:23]
	v_mul_f32_e32 v10, v14, v10
	v_add_f32_e32 v14, 1.0, v64
	v_fma_f32 v10, v10, v14, v60
	v_mul_f32_e32 v14, v55, v24
	v_mul_f32_e32 v11, v14, v11
	v_add_f32_e32 v14, 1.0, v65
	v_fma_f32 v11, v11, v14, v61
	v_mul_f32_e32 v14, v3, v24
	v_mul_f32_e32 v12, v14, v12
	v_add_f32_e32 v14, 1.0, v66
	v_fma_f32 v12, v12, v14, v62
	v_mul_f32_e32 v14, v53, v24
	v_mul_f32_e32 v13, v14, v13
	v_add_f32_e32 v14, 1.0, v67
	v_fmac_f32_e32 v63, v13, v14
	v_cvt_pk_bf16_f32 v10, v10, v11
	v_cvt_pk_bf16_f32 v11, v12, v63
	global_store_dwordx2 v[18:19], v[10:11], off offset:1024
	v_mov_b32_e32 v12, v210
	v_mov_b32_e32 v13, v211
	v_mov_b32_e32 v14, v212
	v_mov_b32_e32 v15, v213
	s_nop 0
	v_mov_b32_e32 v8, v226
	v_mov_b32_e32 v9, v227
	v_mov_b32_e32 v10, v228
	v_mov_b32_e32 v11, v229
	s_nop 0
	v_mov_b32_e32 v20, v248
	v_mov_b32_e32 v21, v249
	v_mov_b32_e32 v22, v250
	v_mov_b32_e32 v23, v251
	v_mul_f32_e32 v16, v0, v24
	v_mul_f32_e32 v12, v16, v12
	v_add_f32_e32 v16, 1.0, v20
	v_fma_f32 v8, v12, v16, v8
	v_mul_f32_e32 v12, v54, v24
	v_mul_f32_e32 v12, v12, v13
	v_add_f32_e32 v13, 1.0, v21
	v_fma_f32 v9, v12, v13, v9
	v_mul_f32_e32 v12, v2, v24
	v_mul_f32_e32 v12, v12, v14
	v_add_f32_e32 v13, 1.0, v22
	v_fma_f32 v10, v12, v13, v10
	v_mul_f32_e32 v12, v52, v24
	v_mul_f32_e32 v12, v12, v15
	v_add_f32_e32 v13, 1.0, v23
	v_fmac_f32_e32 v11, v12, v13
	v_cvt_pk_bf16_f32 v8, v8, v9
	v_cvt_pk_bf16_f32 v9, v10, v11
	global_store_dwordx2 v[18:19], v[8:9], off offset:1536
	s_branch .LBB0_1331
